# waves 4-7 relabelled (wave index XOR 3) at kernel entry so each SIMD's two waves carry a balanced number of retention key-tile pairs (0+7, 1+6, 2+5, 3+4)
# baseline (speedup 1.0000x reference)
_Z4mega6Params:
	s_load_dwordx4 s[76:79], s[0:1], 0xc0
	s_mov_b32 s98, s2
	s_add_u32 s2, s0, 0xd0
	s_addc_u32 s3, s1, 0
	v_and_b32_e32 v250, 0x3ff, v0
	v_bfe_u32 v1, v250, 8, 1
	v_mul_u32_u24_e32 v1, 0xc0, v1
	v_xor_b32_e32 v250, v250, v1
	v_writelane_b32 v251, s2, 0
	s_mov_b32 s8, 0
	v_cmp_eq_u32_e64 s[4:5], 0, v250
	v_writelane_b32 v251, s3, 1
	s_mov_b64 s[2:3], exec
	v_writelane_b32 v251, s4, 2
	s_nop 1
	v_writelane_b32 v251, s5, 3
	s_and_b64 s[4:5], s[2:3], s[4:5]
	s_mov_b64 exec, s[4:5]
	s_cbranch_execz .LBB0_2
	v_mov_b32_e32 v2, 0
	v_mov_b32_e32 v3, v2
	v_mov_b32_e32 v4, v2
	v_mov_b32_e32 v5, v2
	v_mov_b32_e32 v1, 0x25000
	ds_write_b128 v1, v[2:5]
